# P66: three more gate/up-epilogue row-sum xor-16 steps via v_permlane16_swap (first batched group)
# baseline (speedup 1.0000x reference)
.LBB0_1253:
	v_lshl_add_u32 v184, s36, 8, v167
	v_ashrrev_i32_e32 v185, 31, v184
	v_or_b32_e32 v180, 16, v184
	v_lshlrev_b64 v[130:131], 6, v[184:185]
	v_ashrrev_i32_e32 v181, 31, v180
	v_or_b32_e32 v176, 32, v184
	v_lshl_add_u64 v[130:131], v[154:155], 0, v[130:131]
	v_lshlrev_b64 v[132:133], 6, v[180:181]
	v_ashrrev_i32_e32 v177, 31, v176
	v_lshl_add_u64 v[132:133], v[154:155], 0, v[132:133]
	global_load_dwordx4 v[186:189], v[130:131], off
	global_load_dwordx4 v[190:193], v[132:133], off
	v_lshlrev_b64 v[130:131], 6, v[176:177]
	v_lshl_add_u64 v[130:131], v[154:155], 0, v[130:131]
	global_load_dwordx4 v[194:197], v[130:131], off
	v_or_b32_e32 v172, 48, v184
	v_ashrrev_i32_e32 v173, 31, v172
	v_lshlrev_b64 v[130:131], 6, v[172:173]
	v_lshl_add_u64 v[130:131], v[154:155], 0, v[130:131]
	global_load_dwordx4 v[198:201], v[130:131], off
	v_add_u32_e32 v168, 0x80, v184
	v_ashrrev_i32_e32 v169, 31, v168
	v_lshlrev_b64 v[130:131], 6, v[168:169]
	v_lshl_add_u64 v[130:131], v[154:155], 0, v[130:131]
	global_load_dwordx4 v[202:205], v[130:131], off
	v_add_u32_e32 v164, 0x90, v184
	v_ashrrev_i32_e32 v165, 31, v164
	v_lshlrev_b64 v[130:131], 6, v[164:165]
	v_lshl_add_u64 v[130:131], v[154:155], 0, v[130:131]
	global_load_dwordx4 v[206:209], v[130:131], off
	v_add_u32_e32 v162, 0xa0, v184
	v_add_u32_e32 v160, 0xb0, v184
	v_ashrrev_i32_e32 v163, 31, v162
	s_lshl_b64 s[20:21], s[20:21], 2
	v_ashrrev_i32_e32 v161, 31, v160
	v_lshlrev_b64 v[130:131], 6, v[162:163]
	s_add_u32 s11, s38, s20
	v_lshlrev_b64 v[132:133], 6, v[160:161]
	v_lshl_add_u64 v[130:131], v[154:155], 0, v[130:131]
	s_addc_u32 s13, s39, s21
	s_lshl_b32 s20, s18, 8
	v_lshl_add_u64 v[132:133], v[154:155], 0, v[132:133]
	global_load_dwordx4 v[210:213], v[130:131], off
	global_load_dwordx4 v[214:217], v[132:133], off
	s_ashr_i32 s21, s20, 31
	s_lshl_b64 s[20:21], s[20:21], 2
	s_add_u32 s11, s11, s20
	s_addc_u32 s13, s13, s21
	s_lshl_b32 s19, s40, 2
	s_add_u32 s20, s11, s19
	s_addc_u32 s21, s13, 0
	v_lshl_add_u64 v[138:139], v[152:153], 2, s[20:21]
	global_load_dwordx4 v[134:137], v[138:139], off offset:16
	global_load_dwordx4 v[142:145], v[138:139], off
	global_load_dwordx4 v[130:133], v[138:139], off offset:528
	s_nop 0
	global_load_dwordx4 v[138:141], v[138:139], off offset:512
	s_lshl_b32 s18, s18, 7
	s_ashr_i32 s19, s18, 31
	s_lshl_b64 s[18:19], s[18:19], 1
	s_lshl_b32 s36, s40, 1
	s_andn2_b64 vcc, exec, s[8:9]
	s_mov_b64 s[8:9], -1
	s_waitcnt vmcnt(0)
	v_mov_b32_e32 v178, v187
	v_mov_b32_e32 v179, v188
	v_mov_b32_e32 v187, v189
	v_pk_add_f32 v[178:179], v[178:179], v[186:187]
	v_mov_b32_e32 v182, v191
	v_mov_b32_e32 v183, v192
	v_mov_b32_e32 v191, v193
	v_mov_b32_e32 v186, v195
	v_mov_b32_e32 v187, v196
	v_mov_b32_e32 v195, v197
	v_add_f32_e32 v161, v178, v179
	v_pk_add_f32 v[178:179], v[182:183], v[190:191]
	v_pk_add_f32 v[182:183], v[186:187], v[194:195]
	v_add_f32_e32 v165, v178, v179
	v_add_f32_e32 v166, v182, v183
	v_mov_b32_e32 v188, v199
	v_mov_b32_e32 v189, v200
	v_mov_b32_e32 v199, v201
	v_pk_add_f32 v[186:187], v[188:189], v[198:199]
	s_waitcnt lgkmcnt(2)
	v_mov_b32_e32 v163, v161
	s_nop 1
	v_permlane16_swap_b32_e32 v161, v163
	v_add_f32_e32 v161, v161, v163
	v_add_f32_e32 v169, v186, v187
	v_mov_b32_e32 v163, v161
	s_waitcnt lgkmcnt(1)
	v_mov_b32_e32 v170, v165
	s_nop 1
	v_permlane16_swap_b32_e32 v165, v170
	v_add_f32_e32 v165, v165, v170
	ds_swizzle_b32 v174, v169 offset:swizzle(SWAP,16)
	s_waitcnt lgkmcnt(1)
	v_mov_b32_e32 v173, v166
	s_nop 1
	v_permlane16_swap_b32_e32 v166, v173
	v_add_f32_e32 v166, v166, v173
	v_permlane32_swap_b32_e32 v161, v163
	v_mov_b32_e32 v170, v165
	v_mov_b32_e32 v173, v166
	v_add_f32_e32 v161, v161, v163
	v_permlane32_swap_b32_e32 v165, v170
	v_permlane32_swap_b32_e32 v166, v173
	v_fmamk_f32 v161, v161, 0x3a800000, v244
	v_add_f32_e32 v163, v165, v170
	v_mov_b32_e32 v178, v203
	v_mov_b32_e32 v179, v204
	v_mov_b32_e32 v203, v205
	v_add_f32_e32 v165, v166, v173
	v_rsq_f32_e32 v190, v161
	v_fmamk_f32 v161, v163, 0x3a800000, v244
	v_pk_add_f32 v[178:179], v[178:179], v[202:203]
	v_rsq_f32_e32 v188, v161
	v_fmamk_f32 v161, v165, 0x3a800000, v244
	v_add_f32_e32 v165, v178, v179
	v_rsq_f32_e32 v186, v161
	s_waitcnt lgkmcnt(0)
	v_add_f32_e32 v161, v169, v174
	v_mov_b32_e32 v163, v161
	s_nop 1
	v_permlane32_swap_b32_e32 v161, v163
	v_add_f32_e32 v161, v161, v163
	v_mov_b32_e32 v178, v207
	v_mov_b32_e32 v179, v208
	v_mov_b32_e32 v207, v209
	v_fmamk_f32 v161, v161, 0x3a800000, v244
	v_pk_add_f32 v[178:179], v[178:179], v[206:207]
	v_rsq_f32_e32 v182, v161
	s_waitcnt lgkmcnt(0)
	v_mov_b32_e32 v166, v165
	s_nop 1
	v_permlane16_swap_b32_e32 v165, v166
	v_add_f32_e32 v161, v165, v166
	v_add_f32_e32 v165, v178, v179
	v_mov_b32_e32 v163, v161
	s_nop 1
	v_permlane32_swap_b32_e32 v161, v163
	v_add_f32_e32 v161, v161, v163
	v_mov_b32_e32 v192, v211
	v_mov_b32_e32 v193, v212
	v_mov_b32_e32 v211, v213
	v_fmamk_f32 v161, v161, 0x3a800000, v244
	v_pk_add_f32 v[192:193], v[192:193], v[210:211]
	v_rsq_f32_e32 v178, v161
	s_waitcnt lgkmcnt(0)
	v_mov_b32_e32 v166, v165
	s_nop 1
	v_permlane16_swap_b32_e32 v165, v166
	v_add_f32_e32 v161, v165, v166
	v_add_f32_e32 v165, v192, v193
	v_mov_b32_e32 v163, v161
	s_nop 1
	v_permlane32_swap_b32_e32 v161, v163
	v_add_f32_e32 v161, v161, v163
	v_mov_b32_e32 v192, v215
	v_mov_b32_e32 v193, v216
	v_mov_b32_e32 v215, v217
	v_fmamk_f32 v161, v161, 0x3a800000, v244
	v_pk_add_f32 v[192:193], v[192:193], v[214:215]
	v_pk_fma_f32 v[126:127], v[126:127], v[190:191], v[142:143] op_sel_hi:[1,0,1]
	v_rsq_f32_e32 v174, v161
	s_waitcnt lgkmcnt(0)
	v_mov_b32_e32 v166, v165
	s_nop 1
	v_permlane16_swap_b32_e32 v165, v166
	v_add_f32_e32 v161, v165, v166
	v_add_f32_e32 v165, v192, v193
	v_pk_mul_f32 v[192:193], v[126:127], s[84:85] op_sel_hi:[1,0]
	v_pk_fma_f32 v[128:129], v[128:129], v[190:191], v[144:145] op_sel_hi:[1,0,1]
	v_exp_f32_e32 v192, v192
	v_exp_f32_e32 v193, v193
	v_pk_mul_f32 v[194:195], v[128:129], s[84:85] op_sel_hi:[1,0]
	v_pk_fma_f32 v[118:119], v[118:119], v[190:191], v[138:139] op_sel_hi:[1,0,1]
	v_exp_f32_e32 v194, v194
	v_pk_add_f32 v[192:193], v[192:193], 1.0 op_sel_hi:[1,0]
	v_exp_f32_e32 v195, v195
	v_rcp_f32_e32 v192, v192
	v_rcp_f32_e32 v193, v193
	v_pk_fma_f32 v[122:123], v[122:123], v[190:191], v[134:135] op_sel_hi:[1,0,1]
	v_pk_fma_f32 v[120:121], v[120:121], v[190:191], v[140:141] op_sel_hi:[1,0,1]
	v_pk_fma_f32 v[124:125], v[124:125], v[190:191], v[136:137] op_sel_hi:[1,0,1]
	v_pk_mul_f32 v[126:127], v[126:127], v[192:193]
	v_pk_mul_f32 v[192:193], v[122:123], s[84:85] op_sel_hi:[1,0]
	v_pk_mul_f32 v[118:119], v[118:119], v[126:127]
	v_pk_add_f32 v[126:127], v[194:195], 1.0 op_sel_hi:[1,0]
	v_exp_f32_e32 v192, v192
	v_rcp_f32_e32 v126, v126
	v_rcp_f32_e32 v127, v127
	v_exp_f32_e32 v193, v193
	v_cvt_pk_bf16_f32 v118, v118, v119
	v_pk_fma_f32 v[114:115], v[114:115], v[190:191], v[130:131] op_sel_hi:[1,0,1]
	v_pk_mul_f32 v[126:127], v[128:129], v[126:127]
	v_pk_mul_f32 v[128:129], v[124:125], s[84:85] op_sel_hi:[1,0]
	v_pk_mul_f32 v[120:121], v[120:121], v[126:127]
	v_pk_add_f32 v[126:127], v[192:193], 1.0 op_sel_hi:[1,0]
	v_exp_f32_e32 v128, v128
	v_rcp_f32_e32 v126, v126
	v_rcp_f32_e32 v127, v127
	v_exp_f32_e32 v129, v129
	v_cvt_pk_bf16_f32 v119, v120, v121
	v_pk_fma_f32 v[110:111], v[110:111], v[188:189], v[142:143] op_sel_hi:[1,0,1]
	v_pk_mul_f32 v[120:121], v[122:123], v[126:127]
	v_pk_add_f32 v[122:123], v[128:129], 1.0 op_sel_hi:[1,0]
	v_pk_mul_f32 v[114:115], v[114:115], v[120:121]
	v_rcp_f32_e32 v122, v122
	v_rcp_f32_e32 v123, v123
	v_cvt_pk_bf16_f32 v120, v114, v115
	v_pk_fma_f32 v[114:115], v[116:117], v[190:191], v[132:133] op_sel_hi:[1,0,1]
	v_pk_fma_f32 v[112:113], v[112:113], v[188:189], v[144:145] op_sel_hi:[1,0,1]
	v_pk_mul_f32 v[116:117], v[124:125], v[122:123]
	v_pk_mul_f32 v[124:125], v[110:111], s[84:85] op_sel_hi:[1,0]
	v_pk_mul_f32 v[114:115], v[114:115], v[116:117]
	v_exp_f32_e32 v124, v124
	v_cvt_pk_bf16_f32 v121, v114, v115
	v_mov_b64_e32 v[114:115], s[4:5]
	v_mad_i64_i32 v[116:117], s[20:21], v184, s72, v[114:115]
	v_exp_f32_e32 v125, v125
	v_lshl_add_u64 v[116:117], v[116:117], 0, s[18:19]
	v_lshl_add_u64 v[122:123], v[116:117], 0, s[36:37]
	v_lshlrev_b64 v[116:117], 1, v[152:153]
	v_lshl_add_u64 v[122:123], v[122:123], 0, v[116:117]
	global_store_dwordx4 v[122:123], v[118:121], off
	v_pk_fma_f32 v[102:103], v[102:103], v[188:189], v[138:139] op_sel_hi:[1,0,1]
	v_pk_fma_f32 v[106:107], v[106:107], v[188:189], v[134:135] op_sel_hi:[1,0,1]
	v_pk_add_f32 v[118:119], v[124:125], 1.0 op_sel_hi:[1,0]
	v_pk_mul_f32 v[120:121], v[112:113], s[84:85] op_sel_hi:[1,0]
	v_rcp_f32_e32 v118, v118
	v_rcp_f32_e32 v119, v119
	v_exp_f32_e32 v120, v120
	v_exp_f32_e32 v121, v121
	v_pk_fma_f32 v[104:105], v[104:105], v[188:189], v[140:141] op_sel_hi:[1,0,1]
	v_pk_mul_f32 v[110:111], v[110:111], v[118:119]
	v_pk_mul_f32 v[118:119], v[106:107], s[84:85] op_sel_hi:[1,0]
	v_pk_mul_f32 v[102:103], v[102:103], v[110:111]
	v_pk_add_f32 v[110:111], v[120:121], 1.0 op_sel_hi:[1,0]
	v_exp_f32_e32 v118, v118
	v_rcp_f32_e32 v110, v110
	v_rcp_f32_e32 v111, v111
	v_exp_f32_e32 v119, v119
	v_pk_fma_f32 v[108:109], v[108:109], v[188:189], v[136:137] op_sel_hi:[1,0,1]
	v_cvt_pk_bf16_f32 v102, v102, v103
	v_pk_mul_f32 v[110:111], v[112:113], v[110:111]
	v_pk_mul_f32 v[112:113], v[108:109], s[84:85] op_sel_hi:[1,0]
	v_pk_mul_f32 v[104:105], v[104:105], v[110:111]
	v_pk_add_f32 v[110:111], v[118:119], 1.0 op_sel_hi:[1,0]
	v_exp_f32_e32 v112, v112
	v_rcp_f32_e32 v110, v110
	v_rcp_f32_e32 v111, v111
	v_exp_f32_e32 v113, v113
	v_cvt_pk_bf16_f32 v103, v104, v105
	v_pk_fma_f32 v[98:99], v[98:99], v[188:189], v[130:131] op_sel_hi:[1,0,1]
	v_pk_mul_f32 v[104:105], v[106:107], v[110:111]
	v_pk_add_f32 v[106:107], v[112:113], 1.0 op_sel_hi:[1,0]
	v_pk_mul_f32 v[98:99], v[98:99], v[104:105]
	v_rcp_f32_e32 v106, v106
	v_rcp_f32_e32 v107, v107
	v_cvt_pk_bf16_f32 v104, v98, v99
	v_pk_fma_f32 v[98:99], v[100:101], v[188:189], v[132:133] op_sel_hi:[1,0,1]
	v_pk_fma_f32 v[94:95], v[94:95], v[186:187], v[142:143] op_sel_hi:[1,0,1]
	v_pk_mul_f32 v[100:101], v[108:109], v[106:107]
	v_pk_fma_f32 v[96:97], v[96:97], v[186:187], v[144:145] op_sel_hi:[1,0,1]
	v_pk_mul_f32 v[98:99], v[98:99], v[100:101]
	v_pk_mul_f32 v[100:101], v[94:95], s[84:85] op_sel_hi:[1,0]
	v_cvt_pk_bf16_f32 v105, v98, v99
	v_mad_i64_i32 v[98:99], s[20:21], v180, s72, v[114:115]
	v_exp_f32_e32 v100, v100
	v_exp_f32_e32 v101, v101
	v_lshl_add_u64 v[98:99], v[98:99], 0, s[18:19]
	v_lshl_add_u64 v[98:99], v[98:99], 0, s[36:37]
	v_lshl_add_u64 v[98:99], v[98:99], 0, v[116:117]
	global_store_dwordx4 v[98:99], v[102:105], off
	v_pk_add_f32 v[98:99], v[100:101], 1.0 op_sel_hi:[1,0]
	v_pk_mul_f32 v[100:101], v[96:97], s[84:85] op_sel_hi:[1,0]
	v_rcp_f32_e32 v98, v98
	v_rcp_f32_e32 v99, v99
	v_exp_f32_e32 v100, v100
	v_exp_f32_e32 v101, v101
	v_pk_fma_f32 v[86:87], v[86:87], v[186:187], v[138:139] op_sel_hi:[1,0,1]
	v_pk_mul_f32 v[94:95], v[94:95], v[98:99]
	v_pk_fma_f32 v[90:91], v[90:91], v[186:187], v[134:135] op_sel_hi:[1,0,1]
	v_pk_mul_f32 v[86:87], v[86:87], v[94:95]
	v_pk_add_f32 v[94:95], v[100:101], 1.0 op_sel_hi:[1,0]
	v_pk_mul_f32 v[98:99], v[90:91], s[84:85] op_sel_hi:[1,0]
	v_rcp_f32_e32 v94, v94
	v_rcp_f32_e32 v95, v95
	v_exp_f32_e32 v98, v98
	v_exp_f32_e32 v99, v99
	v_pk_fma_f32 v[88:89], v[88:89], v[186:187], v[140:141] op_sel_hi:[1,0,1]
	v_pk_mul_f32 v[94:95], v[96:97], v[94:95]
	v_pk_fma_f32 v[92:93], v[92:93], v[186:187], v[136:137] op_sel_hi:[1,0,1]
	v_pk_mul_f32 v[88:89], v[88:89], v[94:95]
	v_pk_add_f32 v[94:95], v[98:99], 1.0 op_sel_hi:[1,0]
	v_pk_mul_f32 v[96:97], v[92:93], s[84:85] op_sel_hi:[1,0]
	v_rcp_f32_e32 v94, v94
	v_rcp_f32_e32 v95, v95
	v_exp_f32_e32 v96, v96
	v_exp_f32_e32 v97, v97
	v_cvt_pk_bf16_f32 v86, v86, v87
	v_cvt_pk_bf16_f32 v87, v88, v89
	v_pk_mul_f32 v[88:89], v[90:91], v[94:95]
	v_pk_add_f32 v[90:91], v[96:97], 1.0 op_sel_hi:[1,0]
	v_pk_fma_f32 v[82:83], v[82:83], v[186:187], v[130:131] op_sel_hi:[1,0,1]
	v_rcp_f32_e32 v90, v90
	v_rcp_f32_e32 v91, v91
	v_pk_mul_f32 v[82:83], v[82:83], v[88:89]
	v_pk_fma_f32 v[78:79], v[78:79], v[182:183], v[142:143] op_sel_hi:[1,0,1]
	v_cvt_pk_bf16_f32 v88, v82, v83
	v_pk_fma_f32 v[82:83], v[84:85], v[186:187], v[132:133] op_sel_hi:[1,0,1]
	v_pk_mul_f32 v[84:85], v[92:93], v[90:91]
	v_pk_fma_f32 v[80:81], v[80:81], v[182:183], v[144:145] op_sel_hi:[1,0,1]
	v_pk_mul_f32 v[82:83], v[82:83], v[84:85]
	v_pk_mul_f32 v[84:85], v[78:79], s[84:85] op_sel_hi:[1,0]
	v_cvt_pk_bf16_f32 v89, v82, v83
	v_mad_i64_i32 v[82:83], s[20:21], v176, s72, v[114:115]
	v_exp_f32_e32 v84, v84
	v_exp_f32_e32 v85, v85
	v_lshl_add_u64 v[82:83], v[82:83], 0, s[18:19]
	v_lshl_add_u64 v[82:83], v[82:83], 0, s[36:37]
	v_lshl_add_u64 v[82:83], v[82:83], 0, v[116:117]
	global_store_dwordx4 v[82:83], v[86:89], off
	v_pk_add_f32 v[82:83], v[84:85], 1.0 op_sel_hi:[1,0]
	v_pk_mul_f32 v[84:85], v[80:81], s[84:85] op_sel_hi:[1,0]
	v_rcp_f32_e32 v82, v82
	v_rcp_f32_e32 v83, v83
	v_exp_f32_e32 v84, v84
	v_exp_f32_e32 v85, v85
	v_pk_fma_f32 v[70:71], v[70:71], v[182:183], v[138:139] op_sel_hi:[1,0,1]
	v_pk_mul_f32 v[78:79], v[78:79], v[82:83]
	v_pk_fma_f32 v[74:75], v[74:75], v[182:183], v[134:135] op_sel_hi:[1,0,1]
	v_pk_mul_f32 v[70:71], v[70:71], v[78:79]
	v_pk_add_f32 v[78:79], v[84:85], 1.0 op_sel_hi:[1,0]
	v_pk_mul_f32 v[82:83], v[74:75], s[84:85] op_sel_hi:[1,0]
	v_rcp_f32_e32 v78, v78
	v_rcp_f32_e32 v79, v79
	v_exp_f32_e32 v82, v82
	v_exp_f32_e32 v83, v83
	v_pk_fma_f32 v[72:73], v[72:73], v[182:183], v[140:141] op_sel_hi:[1,0,1]
	v_pk_mul_f32 v[78:79], v[80:81], v[78:79]
	v_pk_fma_f32 v[76:77], v[76:77], v[182:183], v[136:137] op_sel_hi:[1,0,1]
	v_pk_mul_f32 v[72:73], v[72:73], v[78:79]
	v_pk_add_f32 v[78:79], v[82:83], 1.0 op_sel_hi:[1,0]
	v_pk_mul_f32 v[80:81], v[76:77], s[84:85] op_sel_hi:[1,0]
	v_rcp_f32_e32 v78, v78
	v_rcp_f32_e32 v79, v79
	v_exp_f32_e32 v80, v80
	v_exp_f32_e32 v81, v81
	v_cvt_pk_bf16_f32 v70, v70, v71
	v_cvt_pk_bf16_f32 v71, v72, v73
	v_pk_mul_f32 v[72:73], v[74:75], v[78:79]
	v_pk_add_f32 v[74:75], v[80:81], 1.0 op_sel_hi:[1,0]
	v_pk_fma_f32 v[66:67], v[66:67], v[182:183], v[130:131] op_sel_hi:[1,0,1]
	v_rcp_f32_e32 v74, v74
	v_rcp_f32_e32 v75, v75
	v_pk_mul_f32 v[66:67], v[66:67], v[72:73]
	v_pk_fma_f32 v[62:63], v[62:63], v[178:179], v[142:143] op_sel_hi:[1,0,1]
	v_cvt_pk_bf16_f32 v72, v66, v67
	v_pk_fma_f32 v[66:67], v[68:69], v[182:183], v[132:133] op_sel_hi:[1,0,1]
	v_pk_mul_f32 v[68:69], v[76:77], v[74:75]
	v_pk_fma_f32 v[64:65], v[64:65], v[178:179], v[144:145] op_sel_hi:[1,0,1]
	v_pk_mul_f32 v[66:67], v[66:67], v[68:69]
	v_pk_mul_f32 v[68:69], v[62:63], s[84:85] op_sel_hi:[1,0]
	v_cvt_pk_bf16_f32 v73, v66, v67
	v_mad_i64_i32 v[66:67], s[20:21], v172, s72, v[114:115]
	v_exp_f32_e32 v68, v68
	v_exp_f32_e32 v69, v69
	v_lshl_add_u64 v[66:67], v[66:67], 0, s[18:19]
	v_lshl_add_u64 v[66:67], v[66:67], 0, s[36:37]
	v_lshl_add_u64 v[66:67], v[66:67], 0, v[116:117]
	global_store_dwordx4 v[66:67], v[70:73], off
	v_pk_add_f32 v[66:67], v[68:69], 1.0 op_sel_hi:[1,0]
	v_pk_mul_f32 v[68:69], v[64:65], s[84:85] op_sel_hi:[1,0]
	v_rcp_f32_e32 v66, v66
	v_rcp_f32_e32 v67, v67
	v_exp_f32_e32 v68, v68
	v_exp_f32_e32 v69, v69
	v_pk_fma_f32 v[54:55], v[54:55], v[178:179], v[138:139] op_sel_hi:[1,0,1]
	v_pk_mul_f32 v[62:63], v[62:63], v[66:67]
	v_pk_fma_f32 v[58:59], v[58:59], v[178:179], v[134:135] op_sel_hi:[1,0,1]
	v_pk_mul_f32 v[54:55], v[54:55], v[62:63]
	v_pk_add_f32 v[62:63], v[68:69], 1.0 op_sel_hi:[1,0]
	v_pk_mul_f32 v[66:67], v[58:59], s[84:85] op_sel_hi:[1,0]
	v_rcp_f32_e32 v62, v62
	v_rcp_f32_e32 v63, v63
	v_exp_f32_e32 v66, v66
	v_exp_f32_e32 v67, v67
	v_pk_fma_f32 v[56:57], v[56:57], v[178:179], v[140:141] op_sel_hi:[1,0,1]
	v_pk_mul_f32 v[62:63], v[64:65], v[62:63]
	v_pk_fma_f32 v[60:61], v[60:61], v[178:179], v[136:137] op_sel_hi:[1,0,1]
	v_pk_mul_f32 v[56:57], v[56:57], v[62:63]
	v_pk_add_f32 v[62:63], v[66:67], 1.0 op_sel_hi:[1,0]
	v_pk_mul_f32 v[64:65], v[60:61], s[84:85] op_sel_hi:[1,0]
	v_rcp_f32_e32 v62, v62
	v_rcp_f32_e32 v63, v63
	v_exp_f32_e32 v64, v64
	v_exp_f32_e32 v65, v65
	v_cvt_pk_bf16_f32 v54, v54, v55
	v_cvt_pk_bf16_f32 v55, v56, v57
	v_pk_mul_f32 v[56:57], v[58:59], v[62:63]
	v_pk_add_f32 v[58:59], v[64:65], 1.0 op_sel_hi:[1,0]
	v_pk_fma_f32 v[50:51], v[50:51], v[178:179], v[130:131] op_sel_hi:[1,0,1]
	v_rcp_f32_e32 v58, v58
	v_rcp_f32_e32 v59, v59
	v_pk_mul_f32 v[50:51], v[50:51], v[56:57]
	v_pk_fma_f32 v[46:47], v[46:47], v[174:175], v[142:143] op_sel_hi:[1,0,1]
	v_cvt_pk_bf16_f32 v56, v50, v51
	v_pk_fma_f32 v[50:51], v[52:53], v[178:179], v[132:133] op_sel_hi:[1,0,1]
	v_pk_mul_f32 v[52:53], v[60:61], v[58:59]
	v_pk_fma_f32 v[48:49], v[48:49], v[174:175], v[144:145] op_sel_hi:[1,0,1]
	v_pk_mul_f32 v[50:51], v[50:51], v[52:53]
	v_pk_mul_f32 v[52:53], v[46:47], s[84:85] op_sel_hi:[1,0]
	v_cvt_pk_bf16_f32 v57, v50, v51
	v_mad_i64_i32 v[50:51], s[20:21], v168, s72, v[114:115]
	v_exp_f32_e32 v52, v52
	v_exp_f32_e32 v53, v53
	v_lshl_add_u64 v[50:51], v[50:51], 0, s[18:19]
	v_lshl_add_u64 v[50:51], v[50:51], 0, s[36:37]
	v_lshl_add_u64 v[50:51], v[50:51], 0, v[116:117]
	global_store_dwordx4 v[50:51], v[54:57], off
	v_pk_add_f32 v[50:51], v[52:53], 1.0 op_sel_hi:[1,0]
	v_pk_mul_f32 v[52:53], v[48:49], s[84:85] op_sel_hi:[1,0]
	v_rcp_f32_e32 v50, v50
	v_rcp_f32_e32 v51, v51
	v_exp_f32_e32 v52, v52
	v_exp_f32_e32 v53, v53
	v_pk_fma_f32 v[38:39], v[38:39], v[174:175], v[138:139] op_sel_hi:[1,0,1]
	v_pk_mul_f32 v[46:47], v[46:47], v[50:51]
	v_pk_fma_f32 v[42:43], v[42:43], v[174:175], v[134:135] op_sel_hi:[1,0,1]
	v_pk_mul_f32 v[38:39], v[38:39], v[46:47]
	v_pk_add_f32 v[46:47], v[52:53], 1.0 op_sel_hi:[1,0]
	v_pk_mul_f32 v[50:51], v[42:43], s[84:85] op_sel_hi:[1,0]
	v_rcp_f32_e32 v46, v46
	v_rcp_f32_e32 v47, v47
	v_exp_f32_e32 v50, v50
	v_exp_f32_e32 v51, v51
	v_pk_fma_f32 v[40:41], v[40:41], v[174:175], v[140:141] op_sel_hi:[1,0,1]
	v_pk_mul_f32 v[46:47], v[48:49], v[46:47]
	v_pk_fma_f32 v[44:45], v[44:45], v[174:175], v[136:137] op_sel_hi:[1,0,1]
	v_pk_mul_f32 v[40:41], v[40:41], v[46:47]
	v_pk_add_f32 v[46:47], v[50:51], 1.0 op_sel_hi:[1,0]
	v_pk_mul_f32 v[48:49], v[44:45], s[84:85] op_sel_hi:[1,0]
	v_rcp_f32_e32 v46, v46
	v_rcp_f32_e32 v47, v47
	v_exp_f32_e32 v48, v48
	v_exp_f32_e32 v49, v49
	v_mov_b32_e32 v163, v161
	s_nop 1
	v_permlane32_swap_b32_e32 v161, v163
	v_add_f32_e32 v161, v161, v163
	v_fmamk_f32 v161, v161, 0x3a800000, v244
	v_cvt_pk_bf16_f32 v38, v38, v39
	v_cvt_pk_bf16_f32 v39, v40, v41
	v_pk_mul_f32 v[40:41], v[42:43], v[46:47]
	v_pk_add_f32 v[42:43], v[48:49], 1.0 op_sel_hi:[1,0]
	v_rsq_f32_e32 v170, v161
	v_rcp_f32_e32 v42, v42
	v_rcp_f32_e32 v43, v43
	v_pk_fma_f32 v[34:35], v[34:35], v[174:175], v[130:131] op_sel_hi:[1,0,1]
	v_pk_fma_f32 v[30:31], v[30:31], v[170:171], v[142:143] op_sel_hi:[1,0,1]
	v_pk_mul_f32 v[34:35], v[34:35], v[40:41]
	v_pk_fma_f32 v[32:33], v[32:33], v[170:171], v[144:145] op_sel_hi:[1,0,1]
	v_cvt_pk_bf16_f32 v40, v34, v35
	v_pk_fma_f32 v[34:35], v[36:37], v[174:175], v[132:133] op_sel_hi:[1,0,1]
	v_pk_mul_f32 v[36:37], v[44:45], v[42:43]
	v_pk_fma_f32 v[22:23], v[22:23], v[170:171], v[138:139] op_sel_hi:[1,0,1]
	v_pk_mul_f32 v[34:35], v[34:35], v[36:37]
	v_pk_mul_f32 v[36:37], v[30:31], s[84:85] op_sel_hi:[1,0]
	v_cvt_pk_bf16_f32 v41, v34, v35
	v_mad_i64_i32 v[34:35], s[20:21], v164, s72, v[114:115]
	v_exp_f32_e32 v36, v36
	v_exp_f32_e32 v37, v37
	v_lshl_add_u64 v[34:35], v[34:35], 0, s[18:19]
	v_lshl_add_u64 v[34:35], v[34:35], 0, s[36:37]
	v_lshl_add_u64 v[34:35], v[34:35], 0, v[116:117]
	global_store_dwordx4 v[34:35], v[38:41], off
	v_pk_add_f32 v[34:35], v[36:37], 1.0 op_sel_hi:[1,0]
	v_pk_mul_f32 v[36:37], v[32:33], s[84:85] op_sel_hi:[1,0]
	v_rcp_f32_e32 v34, v34
	v_rcp_f32_e32 v35, v35
	v_exp_f32_e32 v36, v36
	v_exp_f32_e32 v37, v37
	v_pk_fma_f32 v[26:27], v[26:27], v[170:171], v[134:135] op_sel_hi:[1,0,1]
	v_pk_mul_f32 v[30:31], v[30:31], v[34:35]
	v_pk_mul_f32 v[34:35], v[26:27], s[84:85] op_sel_hi:[1,0]
	v_pk_mul_f32 v[22:23], v[22:23], v[30:31]
	v_pk_add_f32 v[30:31], v[36:37], 1.0 op_sel_hi:[1,0]
	ds_swizzle_b32 v166, v165 offset:swizzle(SWAP,16)
	v_rcp_f32_e32 v30, v30
	v_rcp_f32_e32 v31, v31
	v_exp_f32_e32 v34, v34
	v_exp_f32_e32 v35, v35
	v_pk_fma_f32 v[24:25], v[24:25], v[170:171], v[140:141] op_sel_hi:[1,0,1]
	v_pk_mul_f32 v[30:31], v[32:33], v[30:31]
	v_pk_fma_f32 v[28:29], v[28:29], v[170:171], v[136:137] op_sel_hi:[1,0,1]
	v_pk_mul_f32 v[24:25], v[24:25], v[30:31]
	v_pk_add_f32 v[30:31], v[34:35], 1.0 op_sel_hi:[1,0]
	v_pk_mul_f32 v[32:33], v[28:29], s[84:85] op_sel_hi:[1,0]
	s_waitcnt lgkmcnt(0)
	v_add_f32_e32 v161, v165, v166
	v_rcp_f32_e32 v30, v30
	v_rcp_f32_e32 v31, v31
	v_exp_f32_e32 v32, v32
	v_exp_f32_e32 v33, v33
	v_mov_b32_e32 v163, v161
	s_nop 1
	v_permlane32_swap_b32_e32 v161, v163
	v_add_f32_e32 v161, v161, v163
	v_fmamk_f32 v161, v161, 0x3a800000, v244
	v_cvt_pk_bf16_f32 v22, v22, v23
	v_cvt_pk_bf16_f32 v23, v24, v25
	v_pk_mul_f32 v[24:25], v[26:27], v[30:31]
	v_pk_add_f32 v[26:27], v[32:33], 1.0 op_sel_hi:[1,0]
	v_rsq_f32_e32 v166, v161
	v_rcp_f32_e32 v26, v26
	v_rcp_f32_e32 v27, v27
	v_pk_fma_f32 v[18:19], v[18:19], v[170:171], v[130:131] op_sel_hi:[1,0,1]
	v_pk_fma_f32 v[14:15], v[14:15], v[166:167], v[142:143] op_sel_hi:[1,0,1]
	v_pk_mul_f32 v[18:19], v[18:19], v[24:25]
	v_pk_fma_f32 v[16:17], v[16:17], v[166:167], v[144:145] op_sel_hi:[1,0,1]
	v_cvt_pk_bf16_f32 v24, v18, v19
	v_pk_fma_f32 v[18:19], v[20:21], v[170:171], v[132:133] op_sel_hi:[1,0,1]
	v_pk_mul_f32 v[20:21], v[28:29], v[26:27]
	v_pk_fma_f32 v[6:7], v[6:7], v[166:167], v[138:139] op_sel_hi:[1,0,1]
	v_pk_mul_f32 v[18:19], v[18:19], v[20:21]
	v_pk_mul_f32 v[20:21], v[14:15], s[84:85] op_sel_hi:[1,0]
	v_cvt_pk_bf16_f32 v25, v18, v19
	v_mad_i64_i32 v[18:19], s[20:21], v162, s72, v[114:115]
	v_exp_f32_e32 v20, v20
	v_exp_f32_e32 v21, v21
	v_lshl_add_u64 v[18:19], v[18:19], 0, s[18:19]
	v_lshl_add_u64 v[18:19], v[18:19], 0, s[36:37]
	v_lshl_add_u64 v[18:19], v[18:19], 0, v[116:117]
	global_store_dwordx4 v[18:19], v[22:25], off
	v_pk_add_f32 v[18:19], v[20:21], 1.0 op_sel_hi:[1,0]
	v_pk_mul_f32 v[20:21], v[16:17], s[84:85] op_sel_hi:[1,0]
	v_rcp_f32_e32 v18, v18
	v_rcp_f32_e32 v19, v19
	v_exp_f32_e32 v20, v20
	v_exp_f32_e32 v21, v21
	v_pk_fma_f32 v[10:11], v[10:11], v[166:167], v[134:135] op_sel_hi:[1,0,1]
	v_pk_mul_f32 v[14:15], v[14:15], v[18:19]
	v_pk_mul_f32 v[18:19], v[10:11], s[84:85] op_sel_hi:[1,0]
	v_pk_mul_f32 v[6:7], v[6:7], v[14:15]
	v_pk_add_f32 v[14:15], v[20:21], 1.0 op_sel_hi:[1,0]
	v_exp_f32_e32 v18, v18
	v_rcp_f32_e32 v14, v14
	v_rcp_f32_e32 v15, v15
	v_exp_f32_e32 v19, v19
	v_pk_fma_f32 v[8:9], v[8:9], v[166:167], v[140:141] op_sel_hi:[1,0,1]
	v_pk_fma_f32 v[12:13], v[12:13], v[166:167], v[136:137] op_sel_hi:[1,0,1]
	v_pk_mul_f32 v[14:15], v[16:17], v[14:15]
	v_pk_mul_f32 v[16:17], v[12:13], s[84:85] op_sel_hi:[1,0]
	v_pk_mul_f32 v[8:9], v[8:9], v[14:15]
	v_pk_add_f32 v[14:15], v[18:19], 1.0 op_sel_hi:[1,0]
	v_exp_f32_e32 v16, v16
	v_rcp_f32_e32 v14, v14
	v_rcp_f32_e32 v15, v15
	v_exp_f32_e32 v17, v17
	v_cvt_pk_bf16_f32 v6, v6, v7
	v_cvt_pk_bf16_f32 v7, v8, v9
	v_pk_mul_f32 v[8:9], v[10:11], v[14:15]
	v_pk_add_f32 v[10:11], v[16:17], 1.0 op_sel_hi:[1,0]
	v_pk_fma_f32 v[2:3], v[2:3], v[166:167], v[130:131] op_sel_hi:[1,0,1]
	v_rcp_f32_e32 v10, v10
	v_rcp_f32_e32 v11, v11
	v_pk_mul_f32 v[2:3], v[2:3], v[8:9]
	s_nop 0
	v_cvt_pk_bf16_f32 v8, v2, v3
	v_pk_fma_f32 v[2:3], v[4:5], v[166:167], v[132:133] op_sel_hi:[1,0,1]
	v_pk_mul_f32 v[4:5], v[12:13], v[10:11]
	s_nop 0
	v_pk_mul_f32 v[2:3], v[2:3], v[4:5]
	s_nop 0
	v_cvt_pk_bf16_f32 v9, v2, v3
	v_mad_i64_i32 v[2:3], s[20:21], v160, s72, v[114:115]
	v_lshl_add_u64 v[2:3], v[2:3], 0, s[18:19]
	v_lshl_add_u64 v[2:3], v[2:3], 0, s[36:37]
	v_lshl_add_u64 v[2:3], v[2:3], 0, v[116:117]
	global_store_dwordx4 v[2:3], v[6:9], off
	s_cbranch_vccnz .LBB0_1244
	s_andn2_b64 vcc, exec, s[2:3]
	s_cbranch_vccnz .LBB0_1243
	s_barrier
	s_branch .LBB0_1243
